# EpiH1 k_rope tile: the 8 row groups' cos/sin loads issued together at the first group (rows are row0+{0,16,32,48,128,...}); per-group vmcnt(0) waits removed
# baseline (speedup 1.0000x reference)
.LBB0_529:
	s_or_b64 exec, exec, s[92:93]
	s_andn2_b64 vcc, exec, s[62:63]
	s_cbranch_vccnz .LBB0_531
	v_lshlrev_b64 v[128:129], 7, v[154:155]
	v_lshl_add_u64 v[128:129], s[46:47], 0, v[128:129]
	v_lshl_add_u64 v[158:159], v[152:153], 3, v[128:129]
	v_mov_b64_e32 v[250:251], v[158:159]
	global_load_dwordx4 v[182:185], v[250:251], off offset:2064
	global_load_dwordx4 v[186:189], v[250:251], off offset:2048
	v_add_co_u32_e32 v252, vcc, 0x1000, v250
	s_nop 1
	v_addc_co_u32_e32 v253, vcc, 0, v251, vcc
	global_load_dwordx4 v[190:193], v[252:253], off offset:16
	global_load_dwordx4 v[194:197], v[252:253], off
	global_load_dwordx4 v[198:201], v[252:253], off offset:2064
	global_load_dwordx4 v[202:205], v[252:253], off offset:2048
	v_add_co_u32_e32 v248, vcc, 0x4000, v250
	s_nop 1
	v_addc_co_u32_e32 v249, vcc, 0, v251, vcc
	global_load_dwordx4 v[206:209], v[248:249], off offset:16
	global_load_dwordx4 v[210:213], v[248:249], off
	global_load_dwordx4 v[214:217], v[248:249], off offset:2064
	global_load_dwordx4 v[218:221], v[248:249], off offset:2048
	v_add_co_u32_e32 v252, vcc, 0x1000, v248
	s_nop 1
	v_addc_co_u32_e32 v253, vcc, 0, v249, vcc
	global_load_dwordx4 v[222:225], v[252:253], off offset:16
	global_load_dwordx4 v[226:229], v[252:253], off
	global_load_dwordx4 v[230:233], v[252:253], off offset:2064
	global_load_dwordx4 v[234:237], v[252:253], off offset:2048
	global_load_dwordx4 v[128:131], v[158:159], off offset:16
	s_nop 0
	global_load_dwordx4 v[158:161], v[158:159], off
	s_ashr_i32 s89, s88, 31
	s_lshl_b64 s[8:9], s[88:89], 12
	s_waitcnt vmcnt(0)
	v_pk_mul_f32 v[170:171], v[116:117], v[158:159]
	v_pk_mul_f32 v[158:159], v[116:117], v[158:159] op_sel:[0,1] op_sel_hi:[1,0]
	v_pk_mul_f32 v[168:169], v[118:119], v[160:161]
	v_sub_f32_e32 v170, v170, v171
	v_add_f32_e32 v171, v158, v159
	v_pk_mul_f32 v[158:159], v[118:119], v[160:161] op_sel:[0,1] op_sel_hi:[1,0]
	v_pk_mul_f32 v[160:161], v[112:113], v[128:129]
	v_pk_mul_f32 v[128:129], v[112:113], v[128:129] op_sel:[0,1] op_sel_hi:[1,0]
	v_sub_f32_e32 v168, v168, v169
	v_add_f32_e32 v169, v158, v159
	v_pk_mul_f32 v[158:159], v[114:115], v[130:131]
	v_sub_f32_e32 v160, v160, v161
	v_add_f32_e32 v161, v128, v129
	v_pk_mul_f32 v[128:129], v[114:115], v[130:131] op_sel:[0,1] op_sel_hi:[1,0]
	v_sub_f32_e32 v158, v158, v159
	v_add_f32_e32 v131, v128, v129
	v_cvt_pk_bf16_f32 v128, v170, v171
	v_and_b32_e32 v170, 0xfcf, v154
	v_cvt_pk_bf16_f32 v129, v168, v169
	v_cvt_pk_bf16_f32 v130, v160, v161
	v_cvt_pk_bf16_f32 v131, v158, v131
	v_or_b32_e32 v160, s8, v170
	v_mov_b64_e32 v[158:159], s[22:23]
	v_mad_u64_u32 v[168:169], s[10:11], v160, s29, v[158:159]
	s_or_b32 s8, s88, 1
	v_mad_i32_i24 v169, s9, v166, v169
	v_lshlrev_b64 v[160:161], 1, v[150:151]
	s_ashr_i32 s9, s8, 31
	v_lshl_add_u64 v[168:169], v[168:169], 0, v[160:161]
	s_lshl_b64 s[8:9], s[8:9], 12
	global_store_dwordx4 v[168:169], v[128:131], off offset:128
	v_or_b32_e32 v168, s8, v170
	v_mad_u64_u32 v[168:169], s[10:11], v168, s29, v[158:159]
	s_or_b32 s8, s88, 2
	v_mad_i32_i24 v169, s9, v166, v169
	s_ashr_i32 s9, s8, 31
	v_lshl_add_u64 v[168:169], v[168:169], 0, v[160:161]
	s_lshl_b64 s[8:9], s[8:9], 12
	global_store_dwordx4 v[168:169], v[128:131], off offset:128
	v_or_b32_e32 v168, s8, v170
	v_mad_u64_u32 v[168:169], s[10:11], v168, s29, v[158:159]
	s_or_b32 s8, s88, 3
	v_mad_i32_i24 v169, s9, v166, v169
	s_ashr_i32 s9, s8, 31
	v_lshl_add_u64 v[168:169], v[168:169], 0, v[160:161]
	s_lshl_b64 s[8:9], s[8:9], 12
	global_store_dwordx4 v[168:169], v[128:131], off offset:128
	v_or_b32_e32 v168, s8, v170
	v_mad_u64_u32 v[168:169], s[10:11], v168, s29, v[158:159]
	s_or_b32 s8, s88, 4
	v_mad_i32_i24 v169, s9, v166, v169
	s_ashr_i32 s9, s8, 31
	v_lshl_add_u64 v[168:169], v[168:169], 0, v[160:161]
	s_lshl_b64 s[8:9], s[8:9], 12
	global_store_dwordx4 v[168:169], v[128:131], off offset:128
	v_or_b32_e32 v168, s8, v170
	v_mad_u64_u32 v[168:169], s[10:11], v168, s29, v[158:159]
	s_or_b32 s8, s88, 5
	v_mad_i32_i24 v169, s9, v166, v169
	s_ashr_i32 s9, s8, 31
	v_lshl_add_u64 v[168:169], v[168:169], 0, v[160:161]
	s_lshl_b64 s[8:9], s[8:9], 12
	global_store_dwordx4 v[168:169], v[128:131], off offset:128
	v_or_b32_e32 v168, s8, v170
	v_mad_u64_u32 v[168:169], s[10:11], v168, s29, v[158:159]
	s_or_b32 s8, s88, 6
	v_mad_i32_i24 v169, s9, v166, v169
	s_ashr_i32 s9, s8, 31
	v_lshl_add_u64 v[168:169], v[168:169], 0, v[160:161]
	s_lshl_b64 s[92:93], s[8:9], 12
	global_store_dwordx4 v[168:169], v[128:131], off offset:128
	v_or_b32_e32 v168, s92, v170
	v_mad_u64_u32 v[168:169], s[8:9], v168, s29, v[158:159]
	s_or_b32 s8, s69, 7
	v_mad_i32_i24 v169, s93, v166, v169
	s_ashr_i32 s9, s8, 31
	v_lshl_add_u64 v[168:169], v[168:169], 0, v[160:161]
	s_lshl_b64 s[8:9], s[8:9], 12
	global_store_dwordx4 v[168:169], v[128:131], off offset:128
	v_or_b32_e32 v168, s8, v170
	v_mad_u64_u32 v[158:159], s[10:11], v168, s29, v[158:159]
	v_mad_i32_i24 v159, s9, v166, v159
	v_lshl_add_u64 v[158:159], v[158:159], 0, v[160:161]
	global_store_dwordx4 v[158:159], v[128:131], off offset:128

.LBB0_552:
	s_or_b64 exec, exec, s[92:93]
	s_andn2_b64 vcc, exec, s[62:63]
	s_cbranch_vccnz .LBB0_554
	v_lshlrev_b64 v[112:113], 7, v[116:117]
	v_lshl_add_u64 v[112:113], s[46:47], 0, v[112:113]
	v_lshl_add_u64 v[120:121], v[152:153], 3, v[112:113]
	v_mov_b64_e32 v[112:113], v[182:183]
	v_mov_b64_e32 v[114:115], v[184:185]
	s_nop 0
	v_mov_b64_e32 v[120:121], v[186:187]
	v_mov_b64_e32 v[122:123], v[188:189]
	s_ashr_i32 s89, s88, 31
	s_lshl_b64 s[8:9], s[88:89], 12
	v_pk_mul_f32 v[126:127], v[100:101], v[120:121]
	v_pk_mul_f32 v[120:121], v[100:101], v[120:121] op_sel:[0,1] op_sel_hi:[1,0]
	v_pk_mul_f32 v[124:125], v[102:103], v[122:123]
	v_sub_f32_e32 v126, v126, v127
	v_add_f32_e32 v127, v120, v121
	v_pk_mul_f32 v[120:121], v[102:103], v[122:123] op_sel:[0,1] op_sel_hi:[1,0]
	v_pk_mul_f32 v[122:123], v[96:97], v[112:113]
	v_pk_mul_f32 v[112:113], v[96:97], v[112:113] op_sel:[0,1] op_sel_hi:[1,0]
	v_sub_f32_e32 v124, v124, v125
	v_add_f32_e32 v125, v120, v121
	v_pk_mul_f32 v[120:121], v[98:99], v[114:115]
	v_sub_f32_e32 v122, v122, v123
	v_add_f32_e32 v123, v112, v113
	v_pk_mul_f32 v[112:113], v[98:99], v[114:115] op_sel:[0,1] op_sel_hi:[1,0]
	v_sub_f32_e32 v120, v120, v121
	v_add_f32_e32 v115, v112, v113
	v_cvt_pk_bf16_f32 v112, v126, v127
	v_and_b32_e32 v126, 0xfdf, v116
	v_cvt_pk_bf16_f32 v113, v124, v125
	v_cvt_pk_bf16_f32 v114, v122, v123
	v_cvt_pk_bf16_f32 v115, v120, v115
	v_or_b32_e32 v122, s8, v126
	v_mov_b64_e32 v[120:121], s[22:23]
	v_mad_u64_u32 v[124:125], s[10:11], v122, s29, v[120:121]
	s_or_b32 s8, s88, 1
	v_mad_i32_i24 v125, s9, v166, v125
	v_lshlrev_b64 v[122:123], 1, v[150:151]
	s_ashr_i32 s9, s8, 31
	v_lshl_add_u64 v[124:125], v[124:125], 0, v[122:123]
	s_lshl_b64 s[8:9], s[8:9], 12
	global_store_dwordx4 v[124:125], v[112:115], off offset:128
	v_or_b32_e32 v124, s8, v126
	v_mad_u64_u32 v[124:125], s[10:11], v124, s29, v[120:121]
	s_or_b32 s8, s88, 2
	v_mad_i32_i24 v125, s9, v166, v125
	s_ashr_i32 s9, s8, 31
	v_lshl_add_u64 v[124:125], v[124:125], 0, v[122:123]
	s_lshl_b64 s[8:9], s[8:9], 12
	global_store_dwordx4 v[124:125], v[112:115], off offset:128
	v_or_b32_e32 v124, s8, v126
	v_mad_u64_u32 v[124:125], s[10:11], v124, s29, v[120:121]
	s_or_b32 s8, s88, 3
	v_mad_i32_i24 v125, s9, v166, v125
	s_ashr_i32 s9, s8, 31
	v_lshl_add_u64 v[124:125], v[124:125], 0, v[122:123]
	s_lshl_b64 s[8:9], s[8:9], 12
	global_store_dwordx4 v[124:125], v[112:115], off offset:128
	v_or_b32_e32 v124, s8, v126
	v_mad_u64_u32 v[124:125], s[10:11], v124, s29, v[120:121]
	s_or_b32 s8, s88, 4
	v_mad_i32_i24 v125, s9, v166, v125
	s_ashr_i32 s9, s8, 31
	v_lshl_add_u64 v[124:125], v[124:125], 0, v[122:123]
	s_lshl_b64 s[8:9], s[8:9], 12
	global_store_dwordx4 v[124:125], v[112:115], off offset:128
	v_or_b32_e32 v124, s8, v126
	v_mad_u64_u32 v[124:125], s[10:11], v124, s29, v[120:121]
	s_or_b32 s8, s88, 5
	v_mad_i32_i24 v125, s9, v166, v125
	s_ashr_i32 s9, s8, 31
	v_lshl_add_u64 v[124:125], v[124:125], 0, v[122:123]
	s_lshl_b64 s[8:9], s[8:9], 12
	global_store_dwordx4 v[124:125], v[112:115], off offset:128
	v_or_b32_e32 v124, s8, v126
	v_mad_u64_u32 v[124:125], s[10:11], v124, s29, v[120:121]
	s_or_b32 s8, s88, 6
	v_mad_i32_i24 v125, s9, v166, v125
	s_ashr_i32 s9, s8, 31
	v_lshl_add_u64 v[124:125], v[124:125], 0, v[122:123]
	s_lshl_b64 s[92:93], s[8:9], 12
	global_store_dwordx4 v[124:125], v[112:115], off offset:128
	v_or_b32_e32 v124, s92, v126
	v_mad_u64_u32 v[124:125], s[8:9], v124, s29, v[120:121]
	s_or_b32 s8, s69, 7
	v_mad_i32_i24 v125, s93, v166, v125
	s_ashr_i32 s9, s8, 31
	v_lshl_add_u64 v[124:125], v[124:125], 0, v[122:123]
	s_lshl_b64 s[8:9], s[8:9], 12
	global_store_dwordx4 v[124:125], v[112:115], off offset:128
	v_or_b32_e32 v124, s8, v126
	v_mad_u64_u32 v[120:121], s[10:11], v124, s29, v[120:121]
	v_mad_i32_i24 v121, s9, v166, v121
	v_lshl_add_u64 v[120:121], v[120:121], 0, v[122:123]
	global_store_dwordx4 v[120:121], v[112:115], off offset:128

.LBB0_575:
	s_or_b64 exec, exec, s[92:93]
	s_andn2_b64 vcc, exec, s[62:63]
	s_cbranch_vccnz .LBB0_577
	v_lshlrev_b64 v[96:97], 7, v[100:101]
	v_lshl_add_u64 v[96:97], s[46:47], 0, v[96:97]
	v_lshl_add_u64 v[104:105], v[152:153], 3, v[96:97]
	v_mov_b64_e32 v[96:97], v[190:191]
	v_mov_b64_e32 v[98:99], v[192:193]
	s_nop 0
	v_mov_b64_e32 v[104:105], v[194:195]
	v_mov_b64_e32 v[106:107], v[196:197]
	s_ashr_i32 s89, s88, 31
	s_lshl_b64 s[8:9], s[88:89], 12
	v_pk_mul_f32 v[110:111], v[84:85], v[104:105]
	v_pk_mul_f32 v[104:105], v[84:85], v[104:105] op_sel:[0,1] op_sel_hi:[1,0]
	v_pk_mul_f32 v[108:109], v[86:87], v[106:107]
	v_sub_f32_e32 v110, v110, v111
	v_add_f32_e32 v111, v104, v105
	v_pk_mul_f32 v[104:105], v[86:87], v[106:107] op_sel:[0,1] op_sel_hi:[1,0]
	v_pk_mul_f32 v[106:107], v[80:81], v[96:97]
	v_pk_mul_f32 v[96:97], v[80:81], v[96:97] op_sel:[0,1] op_sel_hi:[1,0]
	v_sub_f32_e32 v108, v108, v109
	v_add_f32_e32 v109, v104, v105
	v_pk_mul_f32 v[104:105], v[82:83], v[98:99]
	v_sub_f32_e32 v106, v106, v107
	v_add_f32_e32 v107, v96, v97
	v_pk_mul_f32 v[96:97], v[82:83], v[98:99] op_sel:[0,1] op_sel_hi:[1,0]
	v_sub_f32_e32 v104, v104, v105
	v_add_f32_e32 v99, v96, v97
	v_cvt_pk_bf16_f32 v96, v110, v111
	v_and_b32_e32 v110, 0xfef, v100
	v_cvt_pk_bf16_f32 v97, v108, v109
	v_cvt_pk_bf16_f32 v98, v106, v107
	v_cvt_pk_bf16_f32 v99, v104, v99
	v_or_b32_e32 v106, s8, v110
	v_mov_b64_e32 v[104:105], s[22:23]
	v_mad_u64_u32 v[108:109], s[10:11], v106, s29, v[104:105]
	s_or_b32 s8, s88, 1
	v_mad_i32_i24 v109, s9, v166, v109
	v_lshlrev_b64 v[106:107], 1, v[150:151]
	s_ashr_i32 s9, s8, 31
	v_lshl_add_u64 v[108:109], v[108:109], 0, v[106:107]
	s_lshl_b64 s[8:9], s[8:9], 12
	global_store_dwordx4 v[108:109], v[96:99], off offset:128
	v_or_b32_e32 v108, s8, v110
	v_mad_u64_u32 v[108:109], s[10:11], v108, s29, v[104:105]
	s_or_b32 s8, s88, 2
	v_mad_i32_i24 v109, s9, v166, v109
	s_ashr_i32 s9, s8, 31
	v_lshl_add_u64 v[108:109], v[108:109], 0, v[106:107]
	s_lshl_b64 s[8:9], s[8:9], 12
	global_store_dwordx4 v[108:109], v[96:99], off offset:128
	v_or_b32_e32 v108, s8, v110
	v_mad_u64_u32 v[108:109], s[10:11], v108, s29, v[104:105]
	s_or_b32 s8, s88, 3
	v_mad_i32_i24 v109, s9, v166, v109
	s_ashr_i32 s9, s8, 31
	v_lshl_add_u64 v[108:109], v[108:109], 0, v[106:107]
	s_lshl_b64 s[8:9], s[8:9], 12
	global_store_dwordx4 v[108:109], v[96:99], off offset:128
	v_or_b32_e32 v108, s8, v110
	v_mad_u64_u32 v[108:109], s[10:11], v108, s29, v[104:105]
	s_or_b32 s8, s88, 4
	v_mad_i32_i24 v109, s9, v166, v109
	s_ashr_i32 s9, s8, 31
	v_lshl_add_u64 v[108:109], v[108:109], 0, v[106:107]
	s_lshl_b64 s[8:9], s[8:9], 12
	global_store_dwordx4 v[108:109], v[96:99], off offset:128
	v_or_b32_e32 v108, s8, v110
	v_mad_u64_u32 v[108:109], s[10:11], v108, s29, v[104:105]
	s_or_b32 s8, s88, 5
	v_mad_i32_i24 v109, s9, v166, v109
	s_ashr_i32 s9, s8, 31
	v_lshl_add_u64 v[108:109], v[108:109], 0, v[106:107]
	s_lshl_b64 s[8:9], s[8:9], 12
	global_store_dwordx4 v[108:109], v[96:99], off offset:128
	v_or_b32_e32 v108, s8, v110
	v_mad_u64_u32 v[108:109], s[10:11], v108, s29, v[104:105]
	s_or_b32 s8, s88, 6
	v_mad_i32_i24 v109, s9, v166, v109
	s_ashr_i32 s9, s8, 31
	v_lshl_add_u64 v[108:109], v[108:109], 0, v[106:107]
	s_lshl_b64 s[92:93], s[8:9], 12
	global_store_dwordx4 v[108:109], v[96:99], off offset:128
	v_or_b32_e32 v108, s92, v110
	v_mad_u64_u32 v[108:109], s[8:9], v108, s29, v[104:105]
	s_or_b32 s8, s69, 7
	v_mad_i32_i24 v109, s93, v166, v109
	s_ashr_i32 s9, s8, 31
	v_lshl_add_u64 v[108:109], v[108:109], 0, v[106:107]
	s_lshl_b64 s[8:9], s[8:9], 12
	global_store_dwordx4 v[108:109], v[96:99], off offset:128
	v_or_b32_e32 v108, s8, v110
	v_mad_u64_u32 v[104:105], s[10:11], v108, s29, v[104:105]
	v_mad_i32_i24 v105, s9, v166, v105
	v_lshl_add_u64 v[104:105], v[104:105], 0, v[106:107]
	global_store_dwordx4 v[104:105], v[96:99], off offset:128

.LBB0_598:
	s_or_b64 exec, exec, s[92:93]
	s_andn2_b64 vcc, exec, s[62:63]
	s_cbranch_vccnz .LBB0_600
	v_lshlrev_b64 v[80:81], 7, v[84:85]
	v_lshl_add_u64 v[80:81], s[46:47], 0, v[80:81]
	v_lshl_add_u64 v[88:89], v[152:153], 3, v[80:81]
	v_mov_b64_e32 v[80:81], v[198:199]
	v_mov_b64_e32 v[82:83], v[200:201]
	s_nop 0
	v_mov_b64_e32 v[88:89], v[202:203]
	v_mov_b64_e32 v[90:91], v[204:205]
	s_ashr_i32 s89, s88, 31
	s_lshl_b64 s[8:9], s[88:89], 12
	v_pk_mul_f32 v[94:95], v[68:69], v[88:89]
	v_pk_mul_f32 v[88:89], v[68:69], v[88:89] op_sel:[0,1] op_sel_hi:[1,0]
	v_pk_mul_f32 v[92:93], v[70:71], v[90:91]
	v_sub_f32_e32 v94, v94, v95
	v_add_f32_e32 v95, v88, v89
	v_pk_mul_f32 v[88:89], v[70:71], v[90:91] op_sel:[0,1] op_sel_hi:[1,0]
	v_pk_mul_f32 v[90:91], v[64:65], v[80:81]
	v_pk_mul_f32 v[80:81], v[64:65], v[80:81] op_sel:[0,1] op_sel_hi:[1,0]
	v_sub_f32_e32 v92, v92, v93
	v_add_f32_e32 v93, v88, v89
	v_pk_mul_f32 v[88:89], v[66:67], v[82:83]
	v_sub_f32_e32 v90, v90, v91
	v_add_f32_e32 v91, v80, v81
	v_pk_mul_f32 v[80:81], v[66:67], v[82:83] op_sel:[0,1] op_sel_hi:[1,0]
	v_sub_f32_e32 v88, v88, v89
	v_add_f32_e32 v83, v80, v81
	v_cvt_pk_bf16_f32 v80, v94, v95
	v_and_b32_e32 v94, 0xfff, v84
	v_cvt_pk_bf16_f32 v81, v92, v93
	v_cvt_pk_bf16_f32 v82, v90, v91
	v_cvt_pk_bf16_f32 v83, v88, v83
	v_or_b32_e32 v90, s8, v94
	v_mov_b64_e32 v[88:89], s[22:23]
	v_mad_u64_u32 v[92:93], s[10:11], v90, s29, v[88:89]
	s_or_b32 s8, s88, 1
	v_mad_i32_i24 v93, s9, v166, v93
	v_lshlrev_b64 v[90:91], 1, v[150:151]
	s_ashr_i32 s9, s8, 31
	v_lshl_add_u64 v[92:93], v[92:93], 0, v[90:91]
	s_lshl_b64 s[8:9], s[8:9], 12
	global_store_dwordx4 v[92:93], v[80:83], off offset:128
	v_or_b32_e32 v92, s8, v94
	v_mad_u64_u32 v[92:93], s[10:11], v92, s29, v[88:89]
	s_or_b32 s8, s88, 2
	v_mad_i32_i24 v93, s9, v166, v93
	s_ashr_i32 s9, s8, 31
	v_lshl_add_u64 v[92:93], v[92:93], 0, v[90:91]
	s_lshl_b64 s[8:9], s[8:9], 12
	global_store_dwordx4 v[92:93], v[80:83], off offset:128
	v_or_b32_e32 v92, s8, v94
	v_mad_u64_u32 v[92:93], s[10:11], v92, s29, v[88:89]
	s_or_b32 s8, s88, 3
	v_mad_i32_i24 v93, s9, v166, v93
	s_ashr_i32 s9, s8, 31
	v_lshl_add_u64 v[92:93], v[92:93], 0, v[90:91]
	s_lshl_b64 s[8:9], s[8:9], 12
	global_store_dwordx4 v[92:93], v[80:83], off offset:128
	v_or_b32_e32 v92, s8, v94
	v_mad_u64_u32 v[92:93], s[10:11], v92, s29, v[88:89]
	s_or_b32 s8, s88, 4
	v_mad_i32_i24 v93, s9, v166, v93
	s_ashr_i32 s9, s8, 31
	v_lshl_add_u64 v[92:93], v[92:93], 0, v[90:91]
	s_lshl_b64 s[8:9], s[8:9], 12
	global_store_dwordx4 v[92:93], v[80:83], off offset:128
	v_or_b32_e32 v92, s8, v94
	v_mad_u64_u32 v[92:93], s[10:11], v92, s29, v[88:89]
	s_or_b32 s8, s88, 5
	v_mad_i32_i24 v93, s9, v166, v93
	s_ashr_i32 s9, s8, 31
	v_lshl_add_u64 v[92:93], v[92:93], 0, v[90:91]
	s_lshl_b64 s[8:9], s[8:9], 12
	global_store_dwordx4 v[92:93], v[80:83], off offset:128
	v_or_b32_e32 v92, s8, v94
	v_mad_u64_u32 v[92:93], s[10:11], v92, s29, v[88:89]
	s_or_b32 s8, s88, 6
	v_mad_i32_i24 v93, s9, v166, v93
	s_ashr_i32 s9, s8, 31
	v_lshl_add_u64 v[92:93], v[92:93], 0, v[90:91]
	s_lshl_b64 s[88:89], s[8:9], 12
	global_store_dwordx4 v[92:93], v[80:83], off offset:128
	v_or_b32_e32 v92, s88, v94
	v_mad_u64_u32 v[92:93], s[8:9], v92, s29, v[88:89]
	s_or_b32 s8, s69, 7
	v_mad_i32_i24 v93, s89, v166, v93
	s_ashr_i32 s9, s8, 31
	v_lshl_add_u64 v[92:93], v[92:93], 0, v[90:91]
	s_lshl_b64 s[8:9], s[8:9], 12
	global_store_dwordx4 v[92:93], v[80:83], off offset:128
	v_or_b32_e32 v92, s8, v94
	v_mad_u64_u32 v[88:89], s[10:11], v92, s29, v[88:89]
	v_mad_i32_i24 v89, s9, v166, v89
	v_lshl_add_u64 v[88:89], v[88:89], 0, v[90:91]
	global_store_dwordx4 v[88:89], v[80:83], off offset:128

.LBB0_621:
	s_or_b64 exec, exec, s[92:93]
	s_andn2_b64 vcc, exec, s[62:63]
	s_cbranch_vccnz .LBB0_623
	v_lshlrev_b64 v[64:65], 7, v[68:69]
	v_lshl_add_u64 v[64:65], s[46:47], 0, v[64:65]
	v_lshl_add_u64 v[72:73], v[152:153], 3, v[64:65]
	v_mov_b64_e32 v[64:65], v[206:207]
	v_mov_b64_e32 v[66:67], v[208:209]
	s_nop 0
	v_mov_b64_e32 v[72:73], v[210:211]
	v_mov_b64_e32 v[74:75], v[212:213]
	s_ashr_i32 s89, s88, 31
	s_lshl_b64 s[8:9], s[88:89], 12
	v_pk_mul_f32 v[78:79], v[52:53], v[72:73]
	v_pk_mul_f32 v[72:73], v[52:53], v[72:73] op_sel:[0,1] op_sel_hi:[1,0]
	v_pk_mul_f32 v[76:77], v[54:55], v[74:75]
	v_sub_f32_e32 v78, v78, v79
	v_add_f32_e32 v79, v72, v73
	v_pk_mul_f32 v[72:73], v[54:55], v[74:75] op_sel:[0,1] op_sel_hi:[1,0]
	v_pk_mul_f32 v[74:75], v[48:49], v[64:65]
	v_pk_mul_f32 v[64:65], v[48:49], v[64:65] op_sel:[0,1] op_sel_hi:[1,0]
	v_sub_f32_e32 v76, v76, v77
	v_add_f32_e32 v77, v72, v73
	v_pk_mul_f32 v[72:73], v[50:51], v[66:67]
	v_sub_f32_e32 v74, v74, v75
	v_add_f32_e32 v75, v64, v65
	v_pk_mul_f32 v[64:65], v[50:51], v[66:67] op_sel:[0,1] op_sel_hi:[1,0]
	v_sub_f32_e32 v72, v72, v73
	v_add_f32_e32 v67, v64, v65
	v_cvt_pk_bf16_f32 v64, v78, v79
	v_and_b32_e32 v78, 0xfcf, v68
	v_cvt_pk_bf16_f32 v65, v76, v77
	v_cvt_pk_bf16_f32 v66, v74, v75
	v_cvt_pk_bf16_f32 v67, v72, v67
	v_or_b32_e32 v74, s8, v78
	v_mov_b64_e32 v[72:73], s[22:23]
	v_mad_u64_u32 v[76:77], s[10:11], v74, s29, v[72:73]
	s_or_b32 s8, s88, 1
	v_mad_i32_i24 v77, s9, v166, v77
	v_lshlrev_b64 v[74:75], 1, v[150:151]
	s_ashr_i32 s9, s8, 31
	v_lshl_add_u64 v[76:77], v[76:77], 0, v[74:75]
	s_lshl_b64 s[8:9], s[8:9], 12
	global_store_dwordx4 v[76:77], v[64:67], off offset:128
	v_or_b32_e32 v76, s8, v78
	v_mad_u64_u32 v[76:77], s[10:11], v76, s29, v[72:73]
	s_or_b32 s8, s88, 2
	v_mad_i32_i24 v77, s9, v166, v77
	s_ashr_i32 s9, s8, 31
	v_lshl_add_u64 v[76:77], v[76:77], 0, v[74:75]
	s_lshl_b64 s[8:9], s[8:9], 12
	global_store_dwordx4 v[76:77], v[64:67], off offset:128
	v_or_b32_e32 v76, s8, v78
	v_mad_u64_u32 v[76:77], s[10:11], v76, s29, v[72:73]
	s_or_b32 s8, s88, 3
	v_mad_i32_i24 v77, s9, v166, v77
	s_ashr_i32 s9, s8, 31
	v_lshl_add_u64 v[76:77], v[76:77], 0, v[74:75]
	s_lshl_b64 s[8:9], s[8:9], 12
	global_store_dwordx4 v[76:77], v[64:67], off offset:128
	v_or_b32_e32 v76, s8, v78
	v_mad_u64_u32 v[76:77], s[10:11], v76, s29, v[72:73]
	s_or_b32 s8, s88, 4
	v_mad_i32_i24 v77, s9, v166, v77
	s_ashr_i32 s9, s8, 31
	v_lshl_add_u64 v[76:77], v[76:77], 0, v[74:75]
	s_lshl_b64 s[8:9], s[8:9], 12
	global_store_dwordx4 v[76:77], v[64:67], off offset:128
	v_or_b32_e32 v76, s8, v78
	v_mad_u64_u32 v[76:77], s[10:11], v76, s29, v[72:73]
	s_or_b32 s8, s88, 5
	v_mad_i32_i24 v77, s9, v166, v77
	s_ashr_i32 s9, s8, 31
	v_lshl_add_u64 v[76:77], v[76:77], 0, v[74:75]
	s_lshl_b64 s[8:9], s[8:9], 12
	global_store_dwordx4 v[76:77], v[64:67], off offset:128
	v_or_b32_e32 v76, s8, v78
	v_mad_u64_u32 v[76:77], s[10:11], v76, s29, v[72:73]
	s_or_b32 s8, s88, 6
	v_mad_i32_i24 v77, s9, v166, v77
	s_ashr_i32 s9, s8, 31
	v_lshl_add_u64 v[76:77], v[76:77], 0, v[74:75]
	s_lshl_b64 s[92:93], s[8:9], 12
	global_store_dwordx4 v[76:77], v[64:67], off offset:128
	v_or_b32_e32 v76, s92, v78
	v_mad_u64_u32 v[76:77], s[8:9], v76, s29, v[72:73]
	s_or_b32 s8, s27, 7
	v_mad_i32_i24 v77, s93, v166, v77
	s_ashr_i32 s9, s8, 31
	v_lshl_add_u64 v[76:77], v[76:77], 0, v[74:75]
	s_lshl_b64 s[8:9], s[8:9], 12
	global_store_dwordx4 v[76:77], v[64:67], off offset:128
	v_or_b32_e32 v76, s8, v78
	v_mad_u64_u32 v[72:73], s[10:11], v76, s29, v[72:73]
	v_mad_i32_i24 v73, s9, v166, v73
	v_lshl_add_u64 v[72:73], v[72:73], 0, v[74:75]
	global_store_dwordx4 v[72:73], v[64:67], off offset:128

.LBB0_644:
	s_or_b64 exec, exec, s[92:93]
	s_andn2_b64 vcc, exec, s[62:63]
	s_cbranch_vccnz .LBB0_646
	v_lshlrev_b64 v[48:49], 7, v[52:53]
	v_lshl_add_u64 v[48:49], s[46:47], 0, v[48:49]
	v_lshl_add_u64 v[56:57], v[152:153], 3, v[48:49]
	v_mov_b64_e32 v[48:49], v[214:215]
	v_mov_b64_e32 v[50:51], v[216:217]
	s_nop 0
	v_mov_b64_e32 v[56:57], v[218:219]
	v_mov_b64_e32 v[58:59], v[220:221]
	s_ashr_i32 s89, s88, 31
	s_lshl_b64 s[8:9], s[88:89], 12
	v_pk_mul_f32 v[62:63], v[36:37], v[56:57]
	v_pk_mul_f32 v[56:57], v[36:37], v[56:57] op_sel:[0,1] op_sel_hi:[1,0]
	v_pk_mul_f32 v[60:61], v[38:39], v[58:59]
	v_sub_f32_e32 v62, v62, v63
	v_add_f32_e32 v63, v56, v57
	v_pk_mul_f32 v[56:57], v[38:39], v[58:59] op_sel:[0,1] op_sel_hi:[1,0]
	v_pk_mul_f32 v[58:59], v[32:33], v[48:49]
	v_pk_mul_f32 v[48:49], v[32:33], v[48:49] op_sel:[0,1] op_sel_hi:[1,0]
	v_sub_f32_e32 v60, v60, v61
	v_add_f32_e32 v61, v56, v57
	v_pk_mul_f32 v[56:57], v[34:35], v[50:51]
	v_sub_f32_e32 v58, v58, v59
	v_add_f32_e32 v59, v48, v49
	v_pk_mul_f32 v[48:49], v[34:35], v[50:51] op_sel:[0,1] op_sel_hi:[1,0]
	v_sub_f32_e32 v56, v56, v57
	v_add_f32_e32 v51, v48, v49
	v_cvt_pk_bf16_f32 v48, v62, v63
	v_and_b32_e32 v62, 0xfdf, v52
	v_cvt_pk_bf16_f32 v49, v60, v61
	v_cvt_pk_bf16_f32 v50, v58, v59
	v_cvt_pk_bf16_f32 v51, v56, v51
	v_or_b32_e32 v58, s8, v62
	v_mov_b64_e32 v[56:57], s[22:23]
	v_mad_u64_u32 v[60:61], s[10:11], v58, s29, v[56:57]
	s_or_b32 s8, s88, 1
	v_mad_i32_i24 v61, s9, v166, v61
	v_lshlrev_b64 v[58:59], 1, v[150:151]
	s_ashr_i32 s9, s8, 31
	v_lshl_add_u64 v[60:61], v[60:61], 0, v[58:59]
	s_lshl_b64 s[8:9], s[8:9], 12
	global_store_dwordx4 v[60:61], v[48:51], off offset:128
	v_or_b32_e32 v60, s8, v62
	v_mad_u64_u32 v[60:61], s[10:11], v60, s29, v[56:57]
	s_or_b32 s8, s88, 2
	v_mad_i32_i24 v61, s9, v166, v61
	s_ashr_i32 s9, s8, 31
	v_lshl_add_u64 v[60:61], v[60:61], 0, v[58:59]
	s_lshl_b64 s[8:9], s[8:9], 12
	global_store_dwordx4 v[60:61], v[48:51], off offset:128
	v_or_b32_e32 v60, s8, v62
	v_mad_u64_u32 v[60:61], s[10:11], v60, s29, v[56:57]
	s_or_b32 s8, s88, 3
	v_mad_i32_i24 v61, s9, v166, v61
	s_ashr_i32 s9, s8, 31
	v_lshl_add_u64 v[60:61], v[60:61], 0, v[58:59]
	s_lshl_b64 s[8:9], s[8:9], 12
	global_store_dwordx4 v[60:61], v[48:51], off offset:128
	v_or_b32_e32 v60, s8, v62
	v_mad_u64_u32 v[60:61], s[10:11], v60, s29, v[56:57]
	s_or_b32 s8, s88, 4
	v_mad_i32_i24 v61, s9, v166, v61
	s_ashr_i32 s9, s8, 31
	v_lshl_add_u64 v[60:61], v[60:61], 0, v[58:59]
	s_lshl_b64 s[8:9], s[8:9], 12
	global_store_dwordx4 v[60:61], v[48:51], off offset:128
	v_or_b32_e32 v60, s8, v62
	v_mad_u64_u32 v[60:61], s[10:11], v60, s29, v[56:57]
	s_or_b32 s8, s88, 5
	v_mad_i32_i24 v61, s9, v166, v61
	s_ashr_i32 s9, s8, 31
	v_lshl_add_u64 v[60:61], v[60:61], 0, v[58:59]
	s_lshl_b64 s[8:9], s[8:9], 12
	global_store_dwordx4 v[60:61], v[48:51], off offset:128
	v_or_b32_e32 v60, s8, v62
	v_mad_u64_u32 v[60:61], s[10:11], v60, s29, v[56:57]
	s_or_b32 s8, s88, 6
	v_mad_i32_i24 v61, s9, v166, v61
	s_ashr_i32 s9, s8, 31
	v_lshl_add_u64 v[60:61], v[60:61], 0, v[58:59]
	s_lshl_b64 s[92:93], s[8:9], 12
	global_store_dwordx4 v[60:61], v[48:51], off offset:128
	v_or_b32_e32 v60, s92, v62
	v_mad_u64_u32 v[60:61], s[8:9], v60, s29, v[56:57]
	s_or_b32 s8, s27, 7
	v_mad_i32_i24 v61, s93, v166, v61
	s_ashr_i32 s9, s8, 31
	v_lshl_add_u64 v[60:61], v[60:61], 0, v[58:59]
	s_lshl_b64 s[8:9], s[8:9], 12
	global_store_dwordx4 v[60:61], v[48:51], off offset:128
	v_or_b32_e32 v60, s8, v62
	v_mad_u64_u32 v[56:57], s[10:11], v60, s29, v[56:57]
	v_mad_i32_i24 v57, s9, v166, v57
	v_lshl_add_u64 v[56:57], v[56:57], 0, v[58:59]
	global_store_dwordx4 v[56:57], v[48:51], off offset:128

.LBB0_667:
	s_or_b64 exec, exec, s[92:93]
	s_andn2_b64 vcc, exec, s[62:63]
	s_cbranch_vccnz .LBB0_669
	v_lshlrev_b64 v[32:33], 7, v[36:37]
	v_lshl_add_u64 v[32:33], s[46:47], 0, v[32:33]
	v_lshl_add_u64 v[40:41], v[152:153], 3, v[32:33]
	v_mov_b64_e32 v[32:33], v[222:223]
	v_mov_b64_e32 v[34:35], v[224:225]
	s_nop 0
	v_mov_b64_e32 v[40:41], v[226:227]
	v_mov_b64_e32 v[42:43], v[228:229]
	s_ashr_i32 s89, s88, 31
	s_lshl_b64 s[8:9], s[88:89], 12
	v_pk_mul_f32 v[46:47], v[20:21], v[40:41]
	v_pk_mul_f32 v[40:41], v[20:21], v[40:41] op_sel:[0,1] op_sel_hi:[1,0]
	v_pk_mul_f32 v[44:45], v[22:23], v[42:43]
	v_sub_f32_e32 v46, v46, v47
	v_add_f32_e32 v47, v40, v41
	v_pk_mul_f32 v[40:41], v[22:23], v[42:43] op_sel:[0,1] op_sel_hi:[1,0]
	v_pk_mul_f32 v[42:43], v[16:17], v[32:33]
	v_pk_mul_f32 v[32:33], v[16:17], v[32:33] op_sel:[0,1] op_sel_hi:[1,0]
	v_sub_f32_e32 v44, v44, v45
	v_add_f32_e32 v45, v40, v41
	v_pk_mul_f32 v[40:41], v[18:19], v[34:35]
	v_sub_f32_e32 v42, v42, v43
	v_add_f32_e32 v43, v32, v33
	v_pk_mul_f32 v[32:33], v[18:19], v[34:35] op_sel:[0,1] op_sel_hi:[1,0]
	v_sub_f32_e32 v40, v40, v41
	v_add_f32_e32 v35, v32, v33
	v_cvt_pk_bf16_f32 v32, v46, v47
	v_and_b32_e32 v46, 0xfef, v36
	v_cvt_pk_bf16_f32 v33, v44, v45
	v_cvt_pk_bf16_f32 v34, v42, v43
	v_cvt_pk_bf16_f32 v35, v40, v35
	v_or_b32_e32 v42, s8, v46
	v_mov_b64_e32 v[40:41], s[22:23]
	v_mad_u64_u32 v[44:45], s[10:11], v42, s29, v[40:41]
	s_or_b32 s8, s88, 1
	v_mad_i32_i24 v45, s9, v166, v45
	v_lshlrev_b64 v[42:43], 1, v[150:151]
	s_ashr_i32 s9, s8, 31
	v_lshl_add_u64 v[44:45], v[44:45], 0, v[42:43]
	s_lshl_b64 s[8:9], s[8:9], 12
	global_store_dwordx4 v[44:45], v[32:35], off offset:128
	v_or_b32_e32 v44, s8, v46
	v_mad_u64_u32 v[44:45], s[10:11], v44, s29, v[40:41]
	s_or_b32 s8, s88, 2
	v_mad_i32_i24 v45, s9, v166, v45
	s_ashr_i32 s9, s8, 31
	v_lshl_add_u64 v[44:45], v[44:45], 0, v[42:43]
	s_lshl_b64 s[8:9], s[8:9], 12
	global_store_dwordx4 v[44:45], v[32:35], off offset:128
	v_or_b32_e32 v44, s8, v46
	v_mad_u64_u32 v[44:45], s[10:11], v44, s29, v[40:41]
	s_or_b32 s8, s88, 3
	v_mad_i32_i24 v45, s9, v166, v45
	s_ashr_i32 s9, s8, 31
	v_lshl_add_u64 v[44:45], v[44:45], 0, v[42:43]
	s_lshl_b64 s[8:9], s[8:9], 12
	global_store_dwordx4 v[44:45], v[32:35], off offset:128
	v_or_b32_e32 v44, s8, v46
	v_mad_u64_u32 v[44:45], s[10:11], v44, s29, v[40:41]
	s_or_b32 s8, s88, 4
	v_mad_i32_i24 v45, s9, v166, v45
	s_ashr_i32 s9, s8, 31
	v_lshl_add_u64 v[44:45], v[44:45], 0, v[42:43]
	s_lshl_b64 s[8:9], s[8:9], 12
	global_store_dwordx4 v[44:45], v[32:35], off offset:128
	v_or_b32_e32 v44, s8, v46
	v_mad_u64_u32 v[44:45], s[10:11], v44, s29, v[40:41]
	s_or_b32 s8, s88, 5
	v_mad_i32_i24 v45, s9, v166, v45
	s_ashr_i32 s9, s8, 31
	v_lshl_add_u64 v[44:45], v[44:45], 0, v[42:43]
	s_lshl_b64 s[8:9], s[8:9], 12
	global_store_dwordx4 v[44:45], v[32:35], off offset:128
	v_or_b32_e32 v44, s8, v46
	v_mad_u64_u32 v[44:45], s[10:11], v44, s29, v[40:41]
	s_or_b32 s8, s88, 6
	v_mad_i32_i24 v45, s9, v166, v45
	s_ashr_i32 s9, s8, 31
	v_lshl_add_u64 v[44:45], v[44:45], 0, v[42:43]
	s_lshl_b64 s[92:93], s[8:9], 12
	global_store_dwordx4 v[44:45], v[32:35], off offset:128
	v_or_b32_e32 v44, s92, v46
	v_mad_u64_u32 v[44:45], s[8:9], v44, s29, v[40:41]
	s_or_b32 s8, s27, 7
	v_mad_i32_i24 v45, s93, v166, v45
	s_ashr_i32 s9, s8, 31
	v_lshl_add_u64 v[44:45], v[44:45], 0, v[42:43]
	s_lshl_b64 s[8:9], s[8:9], 12
	global_store_dwordx4 v[44:45], v[32:35], off offset:128
	v_or_b32_e32 v44, s8, v46
	v_mad_u64_u32 v[40:41], s[10:11], v44, s29, v[40:41]
	v_mad_i32_i24 v41, s9, v166, v41
	v_lshl_add_u64 v[40:41], v[40:41], 0, v[42:43]
	global_store_dwordx4 v[40:41], v[32:35], off offset:128

.LBB0_690:
	s_or_b64 exec, exec, s[90:91]
	s_andn2_b64 vcc, exec, s[62:63]
	s_cbranch_vccnz .LBB0_692
	v_lshlrev_b64 v[16:17], 7, v[20:21]
	v_lshl_add_u64 v[16:17], s[46:47], 0, v[16:17]
	v_lshl_add_u64 v[24:25], v[152:153], 3, v[16:17]
	v_mov_b64_e32 v[16:17], v[230:231]
	v_mov_b64_e32 v[18:19], v[232:233]
	s_nop 0
	v_mov_b64_e32 v[24:25], v[234:235]
	v_mov_b64_e32 v[26:27], v[236:237]
	s_ashr_i32 s89, s88, 31
	s_lshl_b64 s[8:9], s[88:89], 12
	v_pk_mul_f32 v[30:31], v[4:5], v[24:25]
	v_pk_mul_f32 v[24:25], v[4:5], v[24:25] op_sel:[0,1] op_sel_hi:[1,0]
	v_pk_mul_f32 v[28:29], v[6:7], v[26:27]
	v_sub_f32_e32 v30, v30, v31
	v_add_f32_e32 v31, v24, v25
	v_pk_mul_f32 v[24:25], v[6:7], v[26:27] op_sel:[0,1] op_sel_hi:[1,0]
	v_pk_mul_f32 v[26:27], v[0:1], v[16:17]
	v_pk_mul_f32 v[16:17], v[0:1], v[16:17] op_sel:[0,1] op_sel_hi:[1,0]
	v_sub_f32_e32 v28, v28, v29
	v_add_f32_e32 v29, v24, v25
	v_pk_mul_f32 v[24:25], v[2:3], v[18:19]
	v_sub_f32_e32 v26, v26, v27
	v_add_f32_e32 v27, v16, v17
	v_pk_mul_f32 v[16:17], v[2:3], v[18:19] op_sel:[0,1] op_sel_hi:[1,0]
	v_sub_f32_e32 v24, v24, v25
	v_add_f32_e32 v19, v16, v17
	v_cvt_pk_bf16_f32 v16, v30, v31
	v_and_b32_e32 v30, 0xfff, v20
	v_cvt_pk_bf16_f32 v17, v28, v29
	v_cvt_pk_bf16_f32 v18, v26, v27
	v_cvt_pk_bf16_f32 v19, v24, v19
	v_or_b32_e32 v26, s8, v30
	v_mov_b64_e32 v[24:25], s[22:23]
	v_mad_u64_u32 v[28:29], s[10:11], v26, s29, v[24:25]
	s_or_b32 s8, s88, 1
	v_mad_i32_i24 v29, s9, v166, v29
	v_lshlrev_b64 v[26:27], 1, v[150:151]
	s_ashr_i32 s9, s8, 31
	v_lshl_add_u64 v[28:29], v[28:29], 0, v[26:27]
	s_lshl_b64 s[8:9], s[8:9], 12
	global_store_dwordx4 v[28:29], v[16:19], off offset:128
	v_or_b32_e32 v28, s8, v30
	v_mad_u64_u32 v[28:29], s[10:11], v28, s29, v[24:25]
	s_or_b32 s8, s88, 2
	v_mad_i32_i24 v29, s9, v166, v29
	s_ashr_i32 s9, s8, 31
	v_lshl_add_u64 v[28:29], v[28:29], 0, v[26:27]
	s_lshl_b64 s[8:9], s[8:9], 12
	global_store_dwordx4 v[28:29], v[16:19], off offset:128
	v_or_b32_e32 v28, s8, v30
	v_mad_u64_u32 v[28:29], s[10:11], v28, s29, v[24:25]
	s_or_b32 s8, s88, 3
	v_mad_i32_i24 v29, s9, v166, v29
	s_ashr_i32 s9, s8, 31
	v_lshl_add_u64 v[28:29], v[28:29], 0, v[26:27]
	s_lshl_b64 s[8:9], s[8:9], 12
	global_store_dwordx4 v[28:29], v[16:19], off offset:128
	v_or_b32_e32 v28, s8, v30
	v_mad_u64_u32 v[28:29], s[10:11], v28, s29, v[24:25]
	s_or_b32 s8, s88, 4
	v_mad_i32_i24 v29, s9, v166, v29
	s_ashr_i32 s9, s8, 31
	v_lshl_add_u64 v[28:29], v[28:29], 0, v[26:27]
	s_lshl_b64 s[8:9], s[8:9], 12
	global_store_dwordx4 v[28:29], v[16:19], off offset:128
	v_or_b32_e32 v28, s8, v30
	v_mad_u64_u32 v[28:29], s[10:11], v28, s29, v[24:25]
	s_or_b32 s8, s88, 5
	v_mad_i32_i24 v29, s9, v166, v29
	s_ashr_i32 s9, s8, 31
	v_lshl_add_u64 v[28:29], v[28:29], 0, v[26:27]
	s_lshl_b64 s[8:9], s[8:9], 12
	global_store_dwordx4 v[28:29], v[16:19], off offset:128
	v_or_b32_e32 v28, s8, v30
	v_mad_u64_u32 v[28:29], s[10:11], v28, s29, v[24:25]
	s_or_b32 s8, s88, 6
	v_mad_i32_i24 v29, s9, v166, v29
	s_ashr_i32 s9, s8, 31
	v_lshl_add_u64 v[28:29], v[28:29], 0, v[26:27]
	s_lshl_b64 s[88:89], s[8:9], 12
	global_store_dwordx4 v[28:29], v[16:19], off offset:128
	v_or_b32_e32 v28, s88, v30
	v_mad_u64_u32 v[28:29], s[8:9], v28, s29, v[24:25]
	s_or_b32 s8, s27, 7
	v_mad_i32_i24 v29, s89, v166, v29
	s_ashr_i32 s9, s8, 31
	v_lshl_add_u64 v[28:29], v[28:29], 0, v[26:27]
	s_lshl_b64 s[8:9], s[8:9], 12
	global_store_dwordx4 v[28:29], v[16:19], off offset:128
	v_or_b32_e32 v28, s8, v30
	v_mad_u64_u32 v[24:25], s[10:11], v28, s29, v[24:25]
	v_mad_i32_i24 v25, s9, v166, v25
	v_lshl_add_u64 v[24:25], v[24:25], 0, v[26:27]
	global_store_dwordx4 v[24:25], v[16:19], off offset:128
